# P9 reorder guarded by nblk==256 (same schedule as v47); cumulative: P8b epilogue, P0 adaLN pipeline, P10/P4b batching
# speedup vs baseline: 1.0055x; 1.0010x over previous
.LBB0_2085:
	s_or_b64 exec, exec, s[4:5]
	s_andn2_b64 vcc, exec, s[16:17]
	v_readlane_b32 s4, v254, 54
	s_waitcnt lgkmcnt(0)
	s_barrier
	v_readlane_b32 s5, v254, 55
	s_cbranch_vccnz .LBB0_2125
	s_add_u32 s2, s50, 0x38c0000
	s_addc_u32 s7, s51, 0
	v_readlane_b32 s8, v254, 50
	s_mov_b32 s34, s4
	s_add_u32 s4, s50, 0x47f0000
	v_readlane_b32 s9, v254, 51
	s_addc_u32 s5, s51, 0
	s_add_i32 s6, s8, 0xffffff00
	s_lshl_b32 s33, s8, 6
	s_lshl_b32 s56, s34, 6
	s_mov_b32 s9, 0
	s_movk_i32 s57, 0x2000
	s_movk_i32 s78, 0x6000
	s_mov_b64 s[10:11], 0x80
	s_mov_b64 s[12:13], 0x2d3cd780
	s_mov_b64 s[16:17], 0x38c0100
	s_mov_b64 s[18:19], 0x2d34d800
	s_mov_b64 s[20:21], 0x3940100
	s_mov_b64 s[22:23], 0x2d3cd800
	s_mov_b64 s[24:25], 0x38c0180
	s_mov_b64 s[26:27], 0x2d34d880
	s_mov_b64 s[28:29], 0x3940180
	s_mov_b64 s[30:31], 0x100
	v_mov_b32_e32 v129, 0
	s_mov_b64 s[38:39], 0x200000
	s_mov_b32 s79, 0x200000
	s_mov_b64 s[40:41], 0x240000
	s_mov_b32 s80, 0x240000
	s_mov_b64 s[42:43], 0x280000
	s_mov_b32 s81, 0x280000
	s_mov_b64 s[44:45], 0x2c0000
	s_mov_b64 s[52:53], 0x2b3cd780
	s_mov_b64 s[54:55], 0x2b34d800
	s_mov_b64 s[58:59], 0x2b3cd800
	s_mov_b64 s[60:61], 0x2b34d880
	v_mov_b32_e32 v148, 1
	s_mov_b32 s82, s8
	s_mov_b32 s84, s8
	s_mov_b32 s98, s34
	s_mov_b32 s99, s8
	s_cmpk_eq_u32 s34, 0x100
	s_cbranch_scc0 .Lp9_noswap
	s_cmpk_lt_u32 s8, 0x40
	s_cbranch_scc0 .Lp9_noswap
	s_movk_i32 s98, 0xff00
	s_add_i32 s99, s8, 0x100
	s_mov_b32 s82, s99
	s_mov_b32 s84, s99
	s_mov_b32 s6, s8
	s_lshl_b32 s33, s99, 6
